# norm phase: row permutation so that context rows (with their partial-sum round trip) are handled by waves that have 8 rows instead of 9
# speedup vs baseline: 1.0104x; 1.0104x over previous
; __device__ __forceinline__ void norm_phase(KP P, const float* g, const float* MODl, int shc, int scc, bool from_input, int npart) {
;     int tid_ = threadIdx.x, bid_ = blockIdx.x; asm volatile("" : "+v"(tid_)); asm volatile("" : "+s"(bid_));
;     const int lane = tid_ & 63, gw = bid_ * 8 + (tid_ >> 6), NGW = gridDim.x * 8;
;     float* H = (float*)(P->ws + WS_H); bf16_t* XN = (bf16_t*)(P->ws + WS_XN);
;     constexpr int RU = 3;
;     for (int row0 = gw; row0 < M; row0 += RU * NGW) {
;         float4 v[RU][4]; float ss[RU];
; #pragma unroll
;         for (int u = 0; u < RU; ++u) { const int row = row0 + u * NGW; ss[u] = 0.f;
;             if (row < M) { const int b = row / RPB, t = row - b * RPB;
;                 const float4* h = from_input ? (t < SEQ ? (const float4*)(P->x + ((size_t)b * SEQ + t) * DM) : (const float4*)(P->ctx + ((size_t)b * CTXL + (t - SEQ)) * DM)) : (const float4*)(H + (size_t)row * DM);
; #pragma unroll
;                 for (int j = 0; j < 4; ++j) { if (from_input) { const f32x4 t4 = __builtin_nontemporal_load((const f32x4*)h + lane + 64 * j); v[u][j] = make_float4(t4[0], t4[1], t4[2], t4[3]); }
;                     else v[u][j] = h[lane + 64 * j]; } } }
; __global__ void __launch_bounds__(512, 2) mega(Params Pk, int ph_lo, int ph_hi) {
;     ...
;                 const float* g = (s == 0 ? P->g_ffn1 : s == 3 ? P->g_mix : P->g_ffn2) + l * 1024; const int shc = s == 0 ? 0 : s == 3 ? 3 : 6;
;                 norm_phase(P, g, MODl, shc, shc + 1, ph == 1, ph == 1 ? 0 : (s == 8 ? (l == 1 ? 0 : 3) : 10));
.LBB0_346:
	v_readfirstlane_b32 s0, v164
	s_load_dword s2, s[72:73], 0x0
	v_readlane_b32 s18, v254, 18
	v_readlane_b32 s19, v254, 19
	s_lshr_b32 s0, s0, 6
	s_lshl_b32 s6, s98, 3
	s_add_i32 s0, s0, s6
	s_cmp_eq_u32 s22, 3
	s_cselect_b32 s6, 56, 64
	s_mov_b32 s7, 0x6000
	s_cselect_b32 s7, 0x3000, s7
	s_cmp_eq_u32 s22, 0
	s_cselect_b32 s6, 48, s6
	s_cselect_b32 s7, 0, s7
	s_add_u32 s10, s18, s6
	s_addc_u32 s11, s19, 0
	s_load_dwordx2 s[10:11], s[10:11], 0x0
	v_readlane_b32 s8, v254, 26
	v_readlane_b32 s9, v254, 27
	v_readlane_b32 s60, v254, 20
	v_readlane_b32 s61, v254, 21
	v_readlane_b32 s31, v254, 28
	s_cmp_eq_u32 s70, 1
	s_cselect_b32 s3, 0, 10
	s_add_i32 s6, s70, -13
	s_cmp_lt_u32 s6, 12
	s_cselect_b32 s6, 0, 3
	s_cmp_eq_u32 s22, 8
	s_cselect_b32 s3, s6, s3
	s_add_u32 s8, s8, s7
	s_addc_u32 s9, s9, 0
	s_add_u32 s62, s60, 0x4200000
	s_addc_u32 s63, s61, 0
	s_load_dwordx2 s[20:21], s[18:19], 0x0
	s_load_dwordx2 s[18:19], s[18:19], 0x10
	s_lshl_b32 s31, s31, 12
	v_and_b32_e32 v120, 63, v164
	v_lshlrev_b32_e32 v112, 4, v120
	v_lshlrev_b32_e32 v113, 3, v120
	v_xor_b32_e32 v114, 1, v120
	v_lshlrev_b32_e32 v114, 2, v114
	v_xor_b32_e32 v115, 2, v120
	v_lshlrev_b32_e32 v115, 2, v115
	v_xor_b32_e32 v116, 4, v120
	v_lshlrev_b32_e32 v116, 2, v116
	v_xor_b32_e32 v117, 8, v120
	v_lshlrev_b32_e32 v117, 2, v117
	v_xor_b32_e32 v118, 16, v120
	v_lshlrev_b32_e32 v118, 2, v118
	v_xor_b32_e32 v119, 32, v120
	v_lshlrev_b32_e32 v119, 2, v119
	s_waitcnt lgkmcnt(0)
	s_lshl_b32 s2, s2, 3
	s_add_u32 s10, s10, s31
	s_addc_u32 s11, s11, 0
	global_load_dwordx4 v[64:67], v112, s[10:11] offset:0
	global_load_dwordx4 v[68:71], v112, s[10:11] offset:1024
	global_load_dwordx4 v[72:75], v112, s[10:11] offset:2048
	global_load_dwordx4 v[76:79], v112, s[10:11] offset:3072
	s_mov_b32 s22, -1
	s_mov_b32 s23, 4
	s_mov_b32 s12, 0
	s_mov_b32 s13, 0
	s_mov_b32 s14, 0
	s_mov_b32 s15, 0
	s_cmp_eq_u32 s70, 1
	s_cbranch_scc1 .Lnm_fi
	s_mov_b32 s31, s0
	s_sub_u32 s6, s31, 0x2000
	s_cmp_lt_u32 s6, 0x100
	s_cselect_b32 s7, 0x400, 0
	s_sub_u32 s6, s31, 0x2400
	s_cmp_lt_u32 s6, 0x100
	s_cselect_b32 s7, 0xfffffc00, s7
	s_sub_u32 s6, s31, 0x4100
	s_cmp_lt_u32 s6, 0x100
	s_cselect_b32 s7, 0xfffffc00, s7
	s_sub_u32 s6, s31, 0x3d00
	s_cmp_lt_u32 s6, 0x100
	s_cselect_b32 s7, 0x400, s7
	s_add_i32 s7, s31, s7
	s_lshl_b32 s6, s7, 12
	s_add_u32 s64, s60, s6
	s_addc_u32 s65, s61, 0
	global_load_dwordx4 v[0:3], v112, s[64:65] offset:0
	global_load_dwordx4 v[4:7], v112, s[64:65] offset:1024
	global_load_dwordx4 v[8:11], v112, s[64:65] offset:2048
	global_load_dwordx4 v[12:15], v112, s[64:65] offset:3072
	s_add_u32 s23, s23, 4
	s_mov_b32 s12, s23
	s_add_i32 s31, s31, s2
	s_cmp_lt_u32 s31, 0x4200
	s_cbranch_scc0 .Lnm_fh_prod
	s_sub_u32 s6, s31, 0x2000
	s_cmp_lt_u32 s6, 0x100
	s_cselect_b32 s7, 0x400, 0
	s_sub_u32 s6, s31, 0x2400
	s_cmp_lt_u32 s6, 0x100
	s_cselect_b32 s7, 0xfffffc00, s7
	s_sub_u32 s6, s31, 0x4100
	s_cmp_lt_u32 s6, 0x100
	s_cselect_b32 s7, 0xfffffc00, s7
	s_sub_u32 s6, s31, 0x3d00
	s_cmp_lt_u32 s6, 0x100
	s_cselect_b32 s7, 0x400, s7
	s_add_i32 s7, s31, s7
	s_lshl_b32 s6, s7, 12
	s_add_u32 s64, s60, s6
	s_addc_u32 s65, s61, 0
	global_load_dwordx4 v[16:19], v112, s[64:65] offset:0
	global_load_dwordx4 v[20:23], v112, s[64:65] offset:1024
	global_load_dwordx4 v[24:27], v112, s[64:65] offset:2048
	global_load_dwordx4 v[28:31], v112, s[64:65] offset:3072
	s_add_u32 s23, s23, 4
	s_mov_b32 s13, s23
	s_add_i32 s31, s31, s2
	s_cmp_lt_u32 s31, 0x4200
	s_cbranch_scc0 .Lnm_fh_prod
	s_sub_u32 s6, s31, 0x2000
	s_cmp_lt_u32 s6, 0x100
	s_cselect_b32 s7, 0x400, 0
	s_sub_u32 s6, s31, 0x2400
	s_cmp_lt_u32 s6, 0x100
	s_cselect_b32 s7, 0xfffffc00, s7
	s_sub_u32 s6, s31, 0x4100
	s_cmp_lt_u32 s6, 0x100
	s_cselect_b32 s7, 0xfffffc00, s7
	s_sub_u32 s6, s31, 0x3d00
	s_cmp_lt_u32 s6, 0x100
	s_cselect_b32 s7, 0x400, s7
	s_add_i32 s7, s31, s7
	s_lshl_b32 s6, s7, 12
	s_add_u32 s64, s60, s6
	s_addc_u32 s65, s61, 0
	global_load_dwordx4 v[32:35], v112, s[64:65] offset:0
	global_load_dwordx4 v[36:39], v112, s[64:65] offset:1024
	global_load_dwordx4 v[40:43], v112, s[64:65] offset:2048
	global_load_dwordx4 v[44:47], v112, s[64:65] offset:3072
	s_add_u32 s23, s23, 4
	s_mov_b32 s14, s23
	s_add_i32 s31, s31, s2
	s_cmp_lt_u32 s31, 0x4200
	s_cbranch_scc0 .Lnm_fh_prod
	s_sub_u32 s6, s31, 0x2000
	s_cmp_lt_u32 s6, 0x100
	s_cselect_b32 s7, 0x400, 0
	s_sub_u32 s6, s31, 0x2400
	s_cmp_lt_u32 s6, 0x100
	s_cselect_b32 s7, 0xfffffc00, s7
	s_sub_u32 s6, s31, 0x4100
	s_cmp_lt_u32 s6, 0x100
	s_cselect_b32 s7, 0xfffffc00, s7
	s_sub_u32 s6, s31, 0x3d00
	s_cmp_lt_u32 s6, 0x100
	s_cselect_b32 s7, 0x400, s7
	s_add_i32 s7, s31, s7
	s_lshl_b32 s6, s7, 12
	s_add_u32 s64, s60, s6
	s_addc_u32 s65, s61, 0
	global_load_dwordx4 v[48:51], v112, s[64:65] offset:0
	global_load_dwordx4 v[52:55], v112, s[64:65] offset:1024
	global_load_dwordx4 v[56:59], v112, s[64:65] offset:2048
	global_load_dwordx4 v[60:63], v112, s[64:65] offset:3072
	s_add_u32 s23, s23, 4
	s_mov_b32 s15, s23

; __device__ __forceinline__ void norm_phase(KP P, const float* g, const float* MODl, int shc, int scc, bool from_input, int npart) {
;     ...
;             if (row < M) { const int b = row / RPB, t = row - b * RPB, w = t >= SEQ ? 2 : b;
;                 if (t >= SEQ && npart > 0) {
;                     const float4* pp = (const float4*)(P->ws + WS_PART) + (size_t)(b * CTXL + (t - SEQ)) * 256 + lane;
.Lnm_fh0_wdone:
	s_sub_u32 s6, s0, 0x2000
	s_cmp_lt_u32 s6, 0x100
	s_cselect_b32 s66, 0x400, 0
	s_sub_u32 s6, s0, 0x2400
	s_cmp_lt_u32 s6, 0x100
	s_cselect_b32 s66, 0xfffffc00, s66
	s_sub_u32 s6, s0, 0x4100
	s_cmp_lt_u32 s6, 0x100
	s_cselect_b32 s66, 0xfffffc00, s66
	s_sub_u32 s6, s0, 0x3d00
	s_cmp_lt_u32 s6, 0x100
	s_cselect_b32 s66, 0x400, s66
	s_add_i32 s66, s0, s66
	s_cmp_ge_u32 s66, 0x2100
	s_cselect_b32 s6, 1, 0
	s_mul_i32 s7, s6, 0x2100
	s_sub_u32 s7, s66, s7
	s_cmp_ge_u32 s7, 0x2000
	s_cselect_b32 s30, 2, s6
	s_lshl_b32 s31, s66, 12
	s_add_u32 s64, s60, s31
	s_addc_u32 s65, s61, 0
	s_cmp_lt_u32 s7, 0x2000
	s_cbranch_scc1 .Lnm_fh0_nopart
	s_cmp_eq_u32 s3, 0
	s_cbranch_scc1 .Lnm_fh0_nopart
	s_lshl_b32 s6, s6, 8
	s_add_u32 s6, s6, s7
	s_sub_u32 s6, s6, 0x2000
	s_lshl_b32 s6, s6, 12
	s_add_u32 s10, s60, s6
	s_addc_u32 s11, s61, 0
	s_add_u32 s10, s10, 0x10e00000
	s_addc_u32 s11, s11, 0
	s_cmp_eq_u32 s3, 10
	s_cbranch_scc1 .Lnm_fh0_p10
	s_cmp_eq_u32 s3, 3
	s_cbranch_scc1 .Lnm_fh0_p3
	s_mov_b32 s31, s3

; __device__ __forceinline__ unsigned pk2(float lo, float hi) { return (unsigned)f2bf(lo) | ((unsigned)f2bf(hi) << 16); }
; __device__ __forceinline__ void norm_phase(KP P, const float* g, const float* MODl, int shc, int scc, bool from_input, int npart) {
;     ...
; #pragma unroll
;                 for (int j = 0; j < 4; ++j) ss[u] += v[u][j].x * v[u][j].x + v[u][j].y * v[u][j].y + v[u][j].z * v[u][j].z + v[u][j].w * v[u][j].w;
;                 if (from_input || (t >= SEQ && npart > 0)) {
; #pragma unroll
;                     for (int j = 0; j < 4; ++j) ((float4*)(H + (size_t)row * DM))[lane + 64 * j] = v[u][j]; }
;                 const float r = rsqrtf(wave_sum(ss[u]) * (1.f / DM) + 1e-6f);
;                 const float* sh = MODl + w * NMOD + shc * 1024; const float* sc = MODl + w * NMOD + scc * 1024;
; #pragma unroll
;                 for (int j = 0; j < 4; ++j) { const int c = (lane + 64 * j) * 4; const float4 gg = *(const float4*)(g + c), s4 = *(const float4*)(sh + c), c4 = *(const float4*)(sc + c);
;                     uint2 o; o.x = pk2(v[u][j].x * r * gg.x * (1.f + c4.x) + s4.x, v[u][j].y * r * gg.y * (1.f + c4.y) + s4.y);
;                     o.y = pk2(v[u][j].z * r * gg.z * (1.f + c4.z) + s4.z, v[u][j].w * r * gg.w * (1.f + c4.w) + s4.w);
;                     *(uint2*)(XN + (size_t)row * DM + c) = o; } } }
.Lnm_fh0_tabok:
	v_pk_mul_f32 v[120:121], v[0:1], v[0:1]
	v_add_f32_e32 v125, v121, v120
	v_pk_mul_f32 v[120:121], v[2:3], v[2:3]
	v_add_f32_e32 v125, v120, v125
	v_add_f32_e32 v125, v121, v125
	v_pk_mul_f32 v[120:121], v[4:5], v[4:5]
	v_add_f32_e32 v124, v121, v120
	v_pk_mul_f32 v[120:121], v[6:7], v[6:7]
	v_add_f32_e32 v124, v120, v124
	v_add_f32_e32 v124, v121, v124
	v_add_f32_e32 v125, v124, v125
	v_pk_mul_f32 v[120:121], v[8:9], v[8:9]
	v_add_f32_e32 v124, v121, v120
	v_pk_mul_f32 v[120:121], v[10:11], v[10:11]
	v_add_f32_e32 v124, v120, v124
	v_add_f32_e32 v124, v121, v124
	v_add_f32_e32 v125, v124, v125
	v_pk_mul_f32 v[120:121], v[12:13], v[12:13]
	v_add_f32_e32 v124, v121, v120
	v_pk_mul_f32 v[120:121], v[14:15], v[14:15]
	v_add_f32_e32 v124, v120, v124
	v_add_f32_e32 v124, v121, v124
	v_add_f32_e32 v125, v124, v125
	ds_bpermute_b32 v120, v114, v125
	s_waitcnt lgkmcnt(0)
	v_add_f32_e32 v125, v125, v120
	ds_bpermute_b32 v120, v115, v125
	s_waitcnt lgkmcnt(0)
	v_add_f32_e32 v125, v125, v120
	ds_bpermute_b32 v120, v116, v125
	s_waitcnt lgkmcnt(0)
	v_add_f32_e32 v125, v125, v120
	ds_bpermute_b32 v120, v117, v125
	s_waitcnt lgkmcnt(0)
	v_add_f32_e32 v125, v125, v120
	ds_bpermute_b32 v120, v118, v125
	s_waitcnt lgkmcnt(0)
	v_add_f32_e32 v125, v125, v120
	ds_bpermute_b32 v120, v119, v125
	s_waitcnt lgkmcnt(0)
	v_add_f32_e32 v125, v125, v120
	v_fmamk_f32 v125, v125, 0x3a800000, v217
	v_rsq_f32_e32 v122, v125
	s_lshl_b32 s31, s66, 11
	s_add_u32 s6, s62, s31
	s_addc_u32 s7, s63, 0
	v_pk_mul_f32 v[124:125], v[0:1], v[122:123] op_sel_hi:[1,0]
	v_pk_mul_f32 v[124:125], v[64:65], v[124:125]
	v_pk_fma_f32 v[124:125], v[96:97], v[124:125], v[80:81]
	v_pk_mul_f32 v[120:121], v[2:3], v[122:123] op_sel_hi:[1,0]
	v_pk_mul_f32 v[120:121], v[66:67], v[120:121]
	v_pk_fma_f32 v[120:121], v[98:99], v[120:121], v[82:83]
	v_cvt_pk_bf16_f32 v124, v124, v125
	v_cvt_pk_bf16_f32 v125, v120, v121
	global_store_dwordx2 v113, v[124:125], s[6:7] offset:0
	v_pk_mul_f32 v[124:125], v[4:5], v[122:123] op_sel_hi:[1,0]
	v_pk_mul_f32 v[124:125], v[68:69], v[124:125]
	v_pk_fma_f32 v[124:125], v[100:101], v[124:125], v[84:85]
	v_pk_mul_f32 v[120:121], v[6:7], v[122:123] op_sel_hi:[1,0]
	v_pk_mul_f32 v[120:121], v[70:71], v[120:121]
	v_pk_fma_f32 v[120:121], v[102:103], v[120:121], v[86:87]
	v_cvt_pk_bf16_f32 v124, v124, v125
	v_cvt_pk_bf16_f32 v125, v120, v121
	global_store_dwordx2 v113, v[124:125], s[6:7] offset:512
	v_pk_mul_f32 v[124:125], v[8:9], v[122:123] op_sel_hi:[1,0]
	v_pk_mul_f32 v[124:125], v[72:73], v[124:125]
	v_pk_fma_f32 v[124:125], v[104:105], v[124:125], v[88:89]
	v_pk_mul_f32 v[120:121], v[10:11], v[122:123] op_sel_hi:[1,0]
	v_pk_mul_f32 v[120:121], v[74:75], v[120:121]
	v_pk_fma_f32 v[120:121], v[106:107], v[120:121], v[90:91]
	v_cvt_pk_bf16_f32 v124, v124, v125
	v_cvt_pk_bf16_f32 v125, v120, v121
	global_store_dwordx2 v113, v[124:125], s[6:7] offset:1024
	v_pk_mul_f32 v[124:125], v[12:13], v[122:123] op_sel_hi:[1,0]
	v_pk_mul_f32 v[124:125], v[76:77], v[124:125]
	v_pk_fma_f32 v[124:125], v[108:109], v[124:125], v[92:93]
	v_pk_mul_f32 v[120:121], v[14:15], v[122:123] op_sel_hi:[1,0]
	v_pk_mul_f32 v[120:121], v[78:79], v[120:121]
	v_pk_fma_f32 v[120:121], v[110:111], v[120:121], v[94:95]
	v_cvt_pk_bf16_f32 v124, v124, v125
	v_cvt_pk_bf16_f32 v125, v120, v121
	global_store_dwordx2 v113, v[124:125], s[6:7] offset:1536
	s_add_u32 s23, s23, 4
	s_mul_i32 s31, s2, 4
	s_add_i32 s31, s0, s31
	s_cmp_lt_u32 s31, 0x4200
	s_cbranch_scc0 .Lnm_fh0_nopf
	s_sub_u32 s6, s31, 0x2000
	s_cmp_lt_u32 s6, 0x100
	s_cselect_b32 s7, 0x400, 0
	s_sub_u32 s6, s31, 0x2400
	s_cmp_lt_u32 s6, 0x100
	s_cselect_b32 s7, 0xfffffc00, s7
	s_sub_u32 s6, s31, 0x4100
	s_cmp_lt_u32 s6, 0x100
	s_cselect_b32 s7, 0xfffffc00, s7
	s_sub_u32 s6, s31, 0x3d00
	s_cmp_lt_u32 s6, 0x100
	s_cselect_b32 s7, 0x400, s7
	s_add_i32 s7, s31, s7
	s_lshl_b32 s6, s7, 12
	s_add_u32 s64, s60, s6
	s_addc_u32 s65, s61, 0
	global_load_dwordx4 v[0:3], v112, s[64:65] offset:0
	global_load_dwordx4 v[4:7], v112, s[64:65] offset:1024
	global_load_dwordx4 v[8:11], v112, s[64:65] offset:2048
	global_load_dwordx4 v[12:15], v112, s[64:65] offset:3072
	s_add_u32 s23, s23, 4
	s_mov_b32 s12, s23

; __device__ __forceinline__ unsigned pk2(float lo, float hi) { return (unsigned)f2bf(lo) | ((unsigned)f2bf(hi) << 16); }
; __device__ __forceinline__ void norm_phase(KP P, const float* g, const float* MODl, int shc, int scc, bool from_input, int npart) {
;     ...
; #pragma unroll
;                 for (int j = 0; j < 4; ++j) ss[u] += v[u][j].x * v[u][j].x + v[u][j].y * v[u][j].y + v[u][j].z * v[u][j].z + v[u][j].w * v[u][j].w;
;                 if (from_input || (t >= SEQ && npart > 0)) {
; #pragma unroll
;                     for (int j = 0; j < 4; ++j) ((float4*)(H + (size_t)row * DM))[lane + 64 * j] = v[u][j]; }
;                 const float r = rsqrtf(wave_sum(ss[u]) * (1.f / DM) + 1e-6f);
;                 const float* sh = MODl + w * NMOD + shc * 1024; const float* sc = MODl + w * NMOD + scc * 1024;
; #pragma unroll
;                 for (int j = 0; j < 4; ++j) { const int c = (lane + 64 * j) * 4; const float4 gg = *(const float4*)(g + c), s4 = *(const float4*)(sh + c), c4 = *(const float4*)(sc + c);
;                     uint2 o; o.x = pk2(v[u][j].x * r * gg.x * (1.f + c4.x) + s4.x, v[u][j].y * r * gg.y * (1.f + c4.y) + s4.y);
;                     o.y = pk2(v[u][j].z * r * gg.z * (1.f + c4.z) + s4.z, v[u][j].w * r * gg.w * (1.f + c4.w) + s4.w);
;                     *(uint2*)(XN + (size_t)row * DM + c) = o; } } }
.Lnm_fh1_tabok:
	v_pk_mul_f32 v[120:121], v[16:17], v[16:17]
	v_add_f32_e32 v125, v121, v120
	v_pk_mul_f32 v[120:121], v[18:19], v[18:19]
	v_add_f32_e32 v125, v120, v125
	v_add_f32_e32 v125, v121, v125
	v_pk_mul_f32 v[120:121], v[20:21], v[20:21]
	v_add_f32_e32 v124, v121, v120
	v_pk_mul_f32 v[120:121], v[22:23], v[22:23]
	v_add_f32_e32 v124, v120, v124
	v_add_f32_e32 v124, v121, v124
	v_add_f32_e32 v125, v124, v125
	v_pk_mul_f32 v[120:121], v[24:25], v[24:25]
	v_add_f32_e32 v124, v121, v120
	v_pk_mul_f32 v[120:121], v[26:27], v[26:27]
	v_add_f32_e32 v124, v120, v124
	v_add_f32_e32 v124, v121, v124
	v_add_f32_e32 v125, v124, v125
	v_pk_mul_f32 v[120:121], v[28:29], v[28:29]
	v_add_f32_e32 v124, v121, v120
	v_pk_mul_f32 v[120:121], v[30:31], v[30:31]
	v_add_f32_e32 v124, v120, v124
	v_add_f32_e32 v124, v121, v124
	v_add_f32_e32 v125, v124, v125
	ds_bpermute_b32 v120, v114, v125
	s_waitcnt lgkmcnt(0)
	v_add_f32_e32 v125, v125, v120
	ds_bpermute_b32 v120, v115, v125
	s_waitcnt lgkmcnt(0)
	v_add_f32_e32 v125, v125, v120
	ds_bpermute_b32 v120, v116, v125
	s_waitcnt lgkmcnt(0)
	v_add_f32_e32 v125, v125, v120
	ds_bpermute_b32 v120, v117, v125
	s_waitcnt lgkmcnt(0)
	v_add_f32_e32 v125, v125, v120
	ds_bpermute_b32 v120, v118, v125
	s_waitcnt lgkmcnt(0)
	v_add_f32_e32 v125, v125, v120
	ds_bpermute_b32 v120, v119, v125
	s_waitcnt lgkmcnt(0)
	v_add_f32_e32 v125, v125, v120
	v_fmamk_f32 v125, v125, 0x3a800000, v217
	v_rsq_f32_e32 v122, v125
	s_lshl_b32 s31, s66, 11
	s_add_u32 s6, s62, s31
	s_addc_u32 s7, s63, 0
	v_pk_mul_f32 v[124:125], v[16:17], v[122:123] op_sel_hi:[1,0]
	v_pk_mul_f32 v[124:125], v[64:65], v[124:125]
	v_pk_fma_f32 v[124:125], v[96:97], v[124:125], v[80:81]
	v_pk_mul_f32 v[120:121], v[18:19], v[122:123] op_sel_hi:[1,0]
	v_pk_mul_f32 v[120:121], v[66:67], v[120:121]
	v_pk_fma_f32 v[120:121], v[98:99], v[120:121], v[82:83]
	v_cvt_pk_bf16_f32 v124, v124, v125
	v_cvt_pk_bf16_f32 v125, v120, v121
	global_store_dwordx2 v113, v[124:125], s[6:7] offset:0
	v_pk_mul_f32 v[124:125], v[20:21], v[122:123] op_sel_hi:[1,0]
	v_pk_mul_f32 v[124:125], v[68:69], v[124:125]
	v_pk_fma_f32 v[124:125], v[100:101], v[124:125], v[84:85]
	v_pk_mul_f32 v[120:121], v[22:23], v[122:123] op_sel_hi:[1,0]
	v_pk_mul_f32 v[120:121], v[70:71], v[120:121]
	v_pk_fma_f32 v[120:121], v[102:103], v[120:121], v[86:87]
	v_cvt_pk_bf16_f32 v124, v124, v125
	v_cvt_pk_bf16_f32 v125, v120, v121
	global_store_dwordx2 v113, v[124:125], s[6:7] offset:512
	v_pk_mul_f32 v[124:125], v[24:25], v[122:123] op_sel_hi:[1,0]
	v_pk_mul_f32 v[124:125], v[72:73], v[124:125]
	v_pk_fma_f32 v[124:125], v[104:105], v[124:125], v[88:89]
	v_pk_mul_f32 v[120:121], v[26:27], v[122:123] op_sel_hi:[1,0]
	v_pk_mul_f32 v[120:121], v[74:75], v[120:121]
	v_pk_fma_f32 v[120:121], v[106:107], v[120:121], v[90:91]
	v_cvt_pk_bf16_f32 v124, v124, v125
	v_cvt_pk_bf16_f32 v125, v120, v121
	global_store_dwordx2 v113, v[124:125], s[6:7] offset:1024
	v_pk_mul_f32 v[124:125], v[28:29], v[122:123] op_sel_hi:[1,0]
	v_pk_mul_f32 v[124:125], v[76:77], v[124:125]
	v_pk_fma_f32 v[124:125], v[108:109], v[124:125], v[92:93]
	v_pk_mul_f32 v[120:121], v[30:31], v[122:123] op_sel_hi:[1,0]
	v_pk_mul_f32 v[120:121], v[78:79], v[120:121]
	v_pk_fma_f32 v[120:121], v[110:111], v[120:121], v[94:95]
	v_cvt_pk_bf16_f32 v124, v124, v125
	v_cvt_pk_bf16_f32 v125, v120, v121
	global_store_dwordx2 v113, v[124:125], s[6:7] offset:1536
	s_add_u32 s23, s23, 4
	s_mul_i32 s31, s2, 4
	s_add_i32 s31, s0, s31
	s_cmp_lt_u32 s31, 0x4200
	s_cbranch_scc0 .Lnm_fh1_nopf
	s_sub_u32 s6, s31, 0x2000
	s_cmp_lt_u32 s6, 0x100
	s_cselect_b32 s7, 0x400, 0
	s_sub_u32 s6, s31, 0x2400
	s_cmp_lt_u32 s6, 0x100
	s_cselect_b32 s7, 0xfffffc00, s7
	s_sub_u32 s6, s31, 0x4100
	s_cmp_lt_u32 s6, 0x100
	s_cselect_b32 s7, 0xfffffc00, s7
	s_sub_u32 s6, s31, 0x3d00
	s_cmp_lt_u32 s6, 0x100
	s_cselect_b32 s7, 0x400, s7
	s_add_i32 s7, s31, s7
	s_lshl_b32 s6, s7, 12
	s_add_u32 s64, s60, s6
	s_addc_u32 s65, s61, 0
	global_load_dwordx4 v[16:19], v112, s[64:65] offset:0
	global_load_dwordx4 v[20:23], v112, s[64:65] offset:1024
	global_load_dwordx4 v[24:27], v112, s[64:65] offset:2048
	global_load_dwordx4 v[28:31], v112, s[64:65] offset:3072
	s_add_u32 s23, s23, 4
	s_mov_b32 s13, s23

; __device__ __forceinline__ unsigned pk2(float lo, float hi) { return (unsigned)f2bf(lo) | ((unsigned)f2bf(hi) << 16); }
; __device__ __forceinline__ void norm_phase(KP P, const float* g, const float* MODl, int shc, int scc, bool from_input, int npart) {
;     ...
; #pragma unroll
;                 for (int j = 0; j < 4; ++j) ss[u] += v[u][j].x * v[u][j].x + v[u][j].y * v[u][j].y + v[u][j].z * v[u][j].z + v[u][j].w * v[u][j].w;
;                 if (from_input || (t >= SEQ && npart > 0)) {
; #pragma unroll
;                     for (int j = 0; j < 4; ++j) ((float4*)(H + (size_t)row * DM))[lane + 64 * j] = v[u][j]; }
;                 const float r = rsqrtf(wave_sum(ss[u]) * (1.f / DM) + 1e-6f);
;                 const float* sh = MODl + w * NMOD + shc * 1024; const float* sc = MODl + w * NMOD + scc * 1024;
; #pragma unroll
;                 for (int j = 0; j < 4; ++j) { const int c = (lane + 64 * j) * 4; const float4 gg = *(const float4*)(g + c), s4 = *(const float4*)(sh + c), c4 = *(const float4*)(sc + c);
;                     uint2 o; o.x = pk2(v[u][j].x * r * gg.x * (1.f + c4.x) + s4.x, v[u][j].y * r * gg.y * (1.f + c4.y) + s4.y);
;                     o.y = pk2(v[u][j].z * r * gg.z * (1.f + c4.z) + s4.z, v[u][j].w * r * gg.w * (1.f + c4.w) + s4.w);
;                     *(uint2*)(XN + (size_t)row * DM + c) = o; } } }
.Lnm_fh2_tabok:
	v_pk_mul_f32 v[120:121], v[32:33], v[32:33]
	v_add_f32_e32 v125, v121, v120
	v_pk_mul_f32 v[120:121], v[34:35], v[34:35]
	v_add_f32_e32 v125, v120, v125
	v_add_f32_e32 v125, v121, v125
	v_pk_mul_f32 v[120:121], v[36:37], v[36:37]
	v_add_f32_e32 v124, v121, v120
	v_pk_mul_f32 v[120:121], v[38:39], v[38:39]
	v_add_f32_e32 v124, v120, v124
	v_add_f32_e32 v124, v121, v124
	v_add_f32_e32 v125, v124, v125
	v_pk_mul_f32 v[120:121], v[40:41], v[40:41]
	v_add_f32_e32 v124, v121, v120
	v_pk_mul_f32 v[120:121], v[42:43], v[42:43]
	v_add_f32_e32 v124, v120, v124
	v_add_f32_e32 v124, v121, v124
	v_add_f32_e32 v125, v124, v125
	v_pk_mul_f32 v[120:121], v[44:45], v[44:45]
	v_add_f32_e32 v124, v121, v120
	v_pk_mul_f32 v[120:121], v[46:47], v[46:47]
	v_add_f32_e32 v124, v120, v124
	v_add_f32_e32 v124, v121, v124
	v_add_f32_e32 v125, v124, v125
	ds_bpermute_b32 v120, v114, v125
	s_waitcnt lgkmcnt(0)
	v_add_f32_e32 v125, v125, v120
	ds_bpermute_b32 v120, v115, v125
	s_waitcnt lgkmcnt(0)
	v_add_f32_e32 v125, v125, v120
	ds_bpermute_b32 v120, v116, v125
	s_waitcnt lgkmcnt(0)
	v_add_f32_e32 v125, v125, v120
	ds_bpermute_b32 v120, v117, v125
	s_waitcnt lgkmcnt(0)
	v_add_f32_e32 v125, v125, v120
	ds_bpermute_b32 v120, v118, v125
	s_waitcnt lgkmcnt(0)
	v_add_f32_e32 v125, v125, v120
	ds_bpermute_b32 v120, v119, v125
	s_waitcnt lgkmcnt(0)
	v_add_f32_e32 v125, v125, v120
	v_fmamk_f32 v125, v125, 0x3a800000, v217
	v_rsq_f32_e32 v122, v125
	s_lshl_b32 s31, s66, 11
	s_add_u32 s6, s62, s31
	s_addc_u32 s7, s63, 0
	v_pk_mul_f32 v[124:125], v[32:33], v[122:123] op_sel_hi:[1,0]
	v_pk_mul_f32 v[124:125], v[64:65], v[124:125]
	v_pk_fma_f32 v[124:125], v[96:97], v[124:125], v[80:81]
	v_pk_mul_f32 v[120:121], v[34:35], v[122:123] op_sel_hi:[1,0]
	v_pk_mul_f32 v[120:121], v[66:67], v[120:121]
	v_pk_fma_f32 v[120:121], v[98:99], v[120:121], v[82:83]
	v_cvt_pk_bf16_f32 v124, v124, v125
	v_cvt_pk_bf16_f32 v125, v120, v121
	global_store_dwordx2 v113, v[124:125], s[6:7] offset:0
	v_pk_mul_f32 v[124:125], v[36:37], v[122:123] op_sel_hi:[1,0]
	v_pk_mul_f32 v[124:125], v[68:69], v[124:125]
	v_pk_fma_f32 v[124:125], v[100:101], v[124:125], v[84:85]
	v_pk_mul_f32 v[120:121], v[38:39], v[122:123] op_sel_hi:[1,0]
	v_pk_mul_f32 v[120:121], v[70:71], v[120:121]
	v_pk_fma_f32 v[120:121], v[102:103], v[120:121], v[86:87]
	v_cvt_pk_bf16_f32 v124, v124, v125
	v_cvt_pk_bf16_f32 v125, v120, v121
	global_store_dwordx2 v113, v[124:125], s[6:7] offset:512
	v_pk_mul_f32 v[124:125], v[40:41], v[122:123] op_sel_hi:[1,0]
	v_pk_mul_f32 v[124:125], v[72:73], v[124:125]
	v_pk_fma_f32 v[124:125], v[104:105], v[124:125], v[88:89]
	v_pk_mul_f32 v[120:121], v[42:43], v[122:123] op_sel_hi:[1,0]
	v_pk_mul_f32 v[120:121], v[74:75], v[120:121]
	v_pk_fma_f32 v[120:121], v[106:107], v[120:121], v[90:91]
	v_cvt_pk_bf16_f32 v124, v124, v125
	v_cvt_pk_bf16_f32 v125, v120, v121
	global_store_dwordx2 v113, v[124:125], s[6:7] offset:1024
	v_pk_mul_f32 v[124:125], v[44:45], v[122:123] op_sel_hi:[1,0]
	v_pk_mul_f32 v[124:125], v[76:77], v[124:125]
	v_pk_fma_f32 v[124:125], v[108:109], v[124:125], v[92:93]
	v_pk_mul_f32 v[120:121], v[46:47], v[122:123] op_sel_hi:[1,0]
	v_pk_mul_f32 v[120:121], v[78:79], v[120:121]
	v_pk_fma_f32 v[120:121], v[110:111], v[120:121], v[94:95]
	v_cvt_pk_bf16_f32 v124, v124, v125
	v_cvt_pk_bf16_f32 v125, v120, v121
	global_store_dwordx2 v113, v[124:125], s[6:7] offset:1536
	s_add_u32 s23, s23, 4
	s_mul_i32 s31, s2, 4
	s_add_i32 s31, s0, s31
	s_cmp_lt_u32 s31, 0x4200
	s_cbranch_scc0 .Lnm_fh2_nopf
	s_sub_u32 s6, s31, 0x2000
	s_cmp_lt_u32 s6, 0x100
	s_cselect_b32 s7, 0x400, 0
	s_sub_u32 s6, s31, 0x2400
	s_cmp_lt_u32 s6, 0x100
	s_cselect_b32 s7, 0xfffffc00, s7
	s_sub_u32 s6, s31, 0x4100
	s_cmp_lt_u32 s6, 0x100
	s_cselect_b32 s7, 0xfffffc00, s7
	s_sub_u32 s6, s31, 0x3d00
	s_cmp_lt_u32 s6, 0x100
	s_cselect_b32 s7, 0x400, s7
	s_add_i32 s7, s31, s7
	s_lshl_b32 s6, s7, 12
	s_add_u32 s64, s60, s6
	s_addc_u32 s65, s61, 0
	global_load_dwordx4 v[32:35], v112, s[64:65] offset:0
	global_load_dwordx4 v[36:39], v112, s[64:65] offset:1024
	global_load_dwordx4 v[40:43], v112, s[64:65] offset:2048
	global_load_dwordx4 v[44:47], v112, s[64:65] offset:3072
	s_add_u32 s23, s23, 4
	s_mov_b32 s14, s23

; __device__ __forceinline__ unsigned pk2(float lo, float hi) { return (unsigned)f2bf(lo) | ((unsigned)f2bf(hi) << 16); }
; __device__ __forceinline__ void norm_phase(KP P, const float* g, const float* MODl, int shc, int scc, bool from_input, int npart) {
;     ...
; #pragma unroll
;                 for (int j = 0; j < 4; ++j) ss[u] += v[u][j].x * v[u][j].x + v[u][j].y * v[u][j].y + v[u][j].z * v[u][j].z + v[u][j].w * v[u][j].w;
;                 if (from_input || (t >= SEQ && npart > 0)) {
; #pragma unroll
;                     for (int j = 0; j < 4; ++j) ((float4*)(H + (size_t)row * DM))[lane + 64 * j] = v[u][j]; }
;                 const float r = rsqrtf(wave_sum(ss[u]) * (1.f / DM) + 1e-6f);
;                 const float* sh = MODl + w * NMOD + shc * 1024; const float* sc = MODl + w * NMOD + scc * 1024;
; #pragma unroll
;                 for (int j = 0; j < 4; ++j) { const int c = (lane + 64 * j) * 4; const float4 gg = *(const float4*)(g + c), s4 = *(const float4*)(sh + c), c4 = *(const float4*)(sc + c);
;                     uint2 o; o.x = pk2(v[u][j].x * r * gg.x * (1.f + c4.x) + s4.x, v[u][j].y * r * gg.y * (1.f + c4.y) + s4.y);
;                     o.y = pk2(v[u][j].z * r * gg.z * (1.f + c4.z) + s4.z, v[u][j].w * r * gg.w * (1.f + c4.w) + s4.w);
;                     *(uint2*)(XN + (size_t)row * DM + c) = o; } } }
.Lnm_fh3_tabok:
	v_pk_mul_f32 v[120:121], v[48:49], v[48:49]
	v_add_f32_e32 v125, v121, v120
	v_pk_mul_f32 v[120:121], v[50:51], v[50:51]
	v_add_f32_e32 v125, v120, v125
	v_add_f32_e32 v125, v121, v125
	v_pk_mul_f32 v[120:121], v[52:53], v[52:53]
	v_add_f32_e32 v124, v121, v120
	v_pk_mul_f32 v[120:121], v[54:55], v[54:55]
	v_add_f32_e32 v124, v120, v124
	v_add_f32_e32 v124, v121, v124
	v_add_f32_e32 v125, v124, v125
	v_pk_mul_f32 v[120:121], v[56:57], v[56:57]
	v_add_f32_e32 v124, v121, v120
	v_pk_mul_f32 v[120:121], v[58:59], v[58:59]
	v_add_f32_e32 v124, v120, v124
	v_add_f32_e32 v124, v121, v124
	v_add_f32_e32 v125, v124, v125
	v_pk_mul_f32 v[120:121], v[60:61], v[60:61]
	v_add_f32_e32 v124, v121, v120
	v_pk_mul_f32 v[120:121], v[62:63], v[62:63]
	v_add_f32_e32 v124, v120, v124
	v_add_f32_e32 v124, v121, v124
	v_add_f32_e32 v125, v124, v125
	ds_bpermute_b32 v120, v114, v125
	s_waitcnt lgkmcnt(0)
	v_add_f32_e32 v125, v125, v120
	ds_bpermute_b32 v120, v115, v125
	s_waitcnt lgkmcnt(0)
	v_add_f32_e32 v125, v125, v120
	ds_bpermute_b32 v120, v116, v125
	s_waitcnt lgkmcnt(0)
	v_add_f32_e32 v125, v125, v120
	ds_bpermute_b32 v120, v117, v125
	s_waitcnt lgkmcnt(0)
	v_add_f32_e32 v125, v125, v120
	ds_bpermute_b32 v120, v118, v125
	s_waitcnt lgkmcnt(0)
	v_add_f32_e32 v125, v125, v120
	ds_bpermute_b32 v120, v119, v125
	s_waitcnt lgkmcnt(0)
	v_add_f32_e32 v125, v125, v120
	v_fmamk_f32 v125, v125, 0x3a800000, v217
	v_rsq_f32_e32 v122, v125
	s_lshl_b32 s31, s66, 11
	s_add_u32 s6, s62, s31
	s_addc_u32 s7, s63, 0
	v_pk_mul_f32 v[124:125], v[48:49], v[122:123] op_sel_hi:[1,0]
	v_pk_mul_f32 v[124:125], v[64:65], v[124:125]
	v_pk_fma_f32 v[124:125], v[96:97], v[124:125], v[80:81]
	v_pk_mul_f32 v[120:121], v[50:51], v[122:123] op_sel_hi:[1,0]
	v_pk_mul_f32 v[120:121], v[66:67], v[120:121]
	v_pk_fma_f32 v[120:121], v[98:99], v[120:121], v[82:83]
	v_cvt_pk_bf16_f32 v124, v124, v125
	v_cvt_pk_bf16_f32 v125, v120, v121
	global_store_dwordx2 v113, v[124:125], s[6:7] offset:0
	v_pk_mul_f32 v[124:125], v[52:53], v[122:123] op_sel_hi:[1,0]
	v_pk_mul_f32 v[124:125], v[68:69], v[124:125]
	v_pk_fma_f32 v[124:125], v[100:101], v[124:125], v[84:85]
	v_pk_mul_f32 v[120:121], v[54:55], v[122:123] op_sel_hi:[1,0]
	v_pk_mul_f32 v[120:121], v[70:71], v[120:121]
	v_pk_fma_f32 v[120:121], v[102:103], v[120:121], v[86:87]
	v_cvt_pk_bf16_f32 v124, v124, v125
	v_cvt_pk_bf16_f32 v125, v120, v121
	global_store_dwordx2 v113, v[124:125], s[6:7] offset:512
	v_pk_mul_f32 v[124:125], v[56:57], v[122:123] op_sel_hi:[1,0]
	v_pk_mul_f32 v[124:125], v[72:73], v[124:125]
	v_pk_fma_f32 v[124:125], v[104:105], v[124:125], v[88:89]
	v_pk_mul_f32 v[120:121], v[58:59], v[122:123] op_sel_hi:[1,0]
	v_pk_mul_f32 v[120:121], v[74:75], v[120:121]
	v_pk_fma_f32 v[120:121], v[106:107], v[120:121], v[90:91]
	v_cvt_pk_bf16_f32 v124, v124, v125
	v_cvt_pk_bf16_f32 v125, v120, v121
	global_store_dwordx2 v113, v[124:125], s[6:7] offset:1024
	v_pk_mul_f32 v[124:125], v[60:61], v[122:123] op_sel_hi:[1,0]
	v_pk_mul_f32 v[124:125], v[76:77], v[124:125]
	v_pk_fma_f32 v[124:125], v[108:109], v[124:125], v[92:93]
	v_pk_mul_f32 v[120:121], v[62:63], v[122:123] op_sel_hi:[1,0]
	v_pk_mul_f32 v[120:121], v[78:79], v[120:121]
	v_pk_fma_f32 v[120:121], v[110:111], v[120:121], v[94:95]
	v_cvt_pk_bf16_f32 v124, v124, v125
	v_cvt_pk_bf16_f32 v125, v120, v121
	global_store_dwordx2 v113, v[124:125], s[6:7] offset:1536
	s_add_u32 s23, s23, 4
	s_mul_i32 s31, s2, 4
	s_add_i32 s31, s0, s31
	s_cmp_lt_u32 s31, 0x4200
	s_cbranch_scc0 .Lnm_fh3_nopf
	s_sub_u32 s6, s31, 0x2000
	s_cmp_lt_u32 s6, 0x100
	s_cselect_b32 s7, 0x400, 0
	s_sub_u32 s6, s31, 0x2400
	s_cmp_lt_u32 s6, 0x100
	s_cselect_b32 s7, 0xfffffc00, s7
	s_sub_u32 s6, s31, 0x4100
	s_cmp_lt_u32 s6, 0x100
	s_cselect_b32 s7, 0xfffffc00, s7
	s_sub_u32 s6, s31, 0x3d00
	s_cmp_lt_u32 s6, 0x100
	s_cselect_b32 s7, 0x400, s7
	s_add_i32 s7, s31, s7
	s_lshl_b32 s6, s7, 12
	s_add_u32 s64, s60, s6
	s_addc_u32 s65, s61, 0
	global_load_dwordx4 v[48:51], v112, s[64:65] offset:0
	global_load_dwordx4 v[52:55], v112, s[64:65] offset:1024
	global_load_dwordx4 v[56:59], v112, s[64:65] offset:2048
	global_load_dwordx4 v[60:63], v112, s[64:65] offset:3072
	s_add_u32 s23, s23, 4
	s_mov_b32 s15, s23

; __device__ __forceinline__ void norm_phase(KP P, const float* g, const float* MODl, int shc, int scc, bool from_input, int npart) {
;     ...
;     for (int row0 = gw; row0 < M; row0 += RU * NGW) {
.Lnm_done:
	s_mov_b32 s66, 0x31000
	s_mov_b64 s[12:13], 0
